# stack5 with the static attention-phase priority raise given to waves 0-3 instead of waves 4-7 (pairing check)
# speedup vs baseline: 1.0047x; 1.0047x over previous
; #define KA() ([]() __attribute__((always_inline)) { KArgs p_ = (KArgs)__builtin_amdgcn_kernarg_segment_ptr(); asm volatile("" : "+s"(p_)); return p_; }())
; #define PH_IDS() int tid = TID_NOW(); asm volatile("" : "+v"(tid)); const int lane = tid & 63, wave = __builtin_amdgcn_readfirstlane(tid >> 6); int bx = blockIdx.x; asm volatile("" : "+s"(bx)); \
;     const int G = gridDim.x, vcu = (G % 8 == 0) ? (bx % 8) * (G / 8) + bx / 8 : bx, gw = vcu * NWAVES + wave, NGW = G * NWAVES; (void)lane; (void)gw; (void)NGW; (void)vcu
; #define BARRIER() do { KArgs Ab_ = KA(); XcdBarrier b_; b_.bar = (unsigned*)(Ab_->ws + WS_CTL) + CW_BAR; b_.x = xb_xcc_id(); b_.st = (volatile LAS unsigned*)(ldsl + MISC_OFF) + 8; int t_ = TID_NOW(); asm volatile("" : "+v"(t_)); xcd_barrier(b_, t_); } while (0)
; __global__ void __launch_bounds__(NWAVES * 64, 2) hymba_fwd(Args args_unused) {
;     ...
;     const int wave0 = __builtin_amdgcn_readfirstlane((int)threadIdx.x >> 6);
;     ...
;         BARRIER();
;         {
;             KArgs A = KA(); PH_IDS(); unsigned char* ws = A->ws;
.LBB0_231:
	s_or_b64 exec, exec, s[4:5]
	s_mov_b64 s[8:9], s[84:85]
	s_mov_b32 s0, -1
	s_waitcnt lgkmcnt(0)
	s_barrier
	s_mov_b32 s21, s82
	v_mbcnt_lo_u32_b32 v0, s0, 0
	v_mbcnt_hi_u32_b32 v0, s0, v0
	v_or_b32_e32 v247, s83, v0
	s_cmp_ge_u32 s83, 0x100
	s_cbranch_scc1 .Lattn_prio_old
	s_setprio 1
